# P3 k-loop back edge: pointer step, exit test, hook tests and index copy all precomputed in the last MFMA clusters; after the loop-back barrier only a flag test and the branch to the body remain (old h
# baseline (speedup 1.0000x reference)
.Lhook_top:
	s_cmp_eq_u32 s64, 16
	s_cselect_b32 s99, 0, 1
	s_add_i32 s99, s98, s99
	s_lshl_b32 s99, s99, 17
	s_add_u32 s100, s38, 0xba00000
	s_addc_u32 s101, s39, 0
	s_add_u32 s100, s100, s99
	s_addc_u32 s101, s101, 0
	v_lshrrev_b32_e32 v2, 6, v175
	v_mul_u32_u24_e32 v2, 0x3c00, v2
	v_lshl_add_u32 v2, v175, 4, v2
	v_mov_b32_e32 v3, 0
	v_lshl_add_u64 v[2:3], s[100:101], 0, v[2:3]
	s_mov_b64 s[100:101], 0x20000
	v_lshl_add_u64 v[254:255], v[2:3], 0, s[100:101]
	global_load_dwordx4 v[132:135], v[2:3], off
	global_load_dwordx4 v[136:139], v[2:3], off offset:1024
	global_load_dwordx4 v[140:143], v[254:255], off
	global_load_dwordx4 v[188:191], v[254:255], off offset:1024
	v_lshl_add_u64 v[2:3], v[2:3], 0, s[20:21]
	v_lshl_add_u64 v[254:255], v[254:255], 0, s[20:21]
	global_load_dwordx4 v[192:195], v[2:3], off
	global_load_dwordx4 v[196:199], v[2:3], off offset:1024
	global_load_dwordx4 v[200:203], v[254:255], off
	global_load_dwordx4 v[204:207], v[254:255], off offset:1024
	v_lshl_add_u64 v[2:3], v[2:3], 0, s[20:21]
	v_lshl_add_u64 v[254:255], v[254:255], 0, s[20:21]
	global_load_dwordx4 v[208:211], v[2:3], off
	global_load_dwordx4 v[212:215], v[2:3], off offset:1024
	global_load_dwordx4 v[216:219], v[254:255], off
	global_load_dwordx4 v[220:223], v[254:255], off offset:1024
	v_lshl_add_u64 v[2:3], v[2:3], 0, s[20:21]
	v_lshl_add_u64 v[254:255], v[254:255], 0, s[20:21]
	global_load_dwordx4 v[224:227], v[2:3], off
	global_load_dwordx4 v[228:231], v[2:3], off offset:1024
	global_load_dwordx4 v[232:235], v[254:255], off
	global_load_dwordx4 v[236:239], v[254:255], off offset:1024
	v_lshl_add_u64 v[2:3], v[2:3], 0, s[20:21]
	v_lshl_add_u64 v[254:255], v[254:255], 0, s[20:21]
	s_waitcnt vmcnt(12)
	v_lshlrev_b32_e32 v178, 16, v140
	v_and_b32_e32 v179, 0xffff0000, v140
	v_lshlrev_b32_e32 v180, 16, v141
	v_and_b32_e32 v181, 0xffff0000, v141
	v_lshlrev_b32_e32 v182, 16, v142
	v_and_b32_e32 v183, 0xffff0000, v142
	v_lshlrev_b32_e32 v184, 16, v143
	v_and_b32_e32 v185, 0xffff0000, v143
	v_rcp_f32_e32 v178, v178
	v_rcp_f32_e32 v179, v179
	v_rcp_f32_e32 v180, v180
	v_rcp_f32_e32 v181, v181
	v_rcp_f32_e32 v182, v182
	v_rcp_f32_e32 v183, v183
	v_rcp_f32_e32 v184, v184
	v_rcp_f32_e32 v185, v185
	v_lshlrev_b32_e32 v140, 16, v132
	v_and_b32_e32 v141, 0xffff0000, v132
	v_lshlrev_b32_e32 v142, 16, v133
	v_and_b32_e32 v143, 0xffff0000, v133
	v_lshlrev_b32_e32 v132, 16, v134
	v_and_b32_e32 v133, 0xffff0000, v134
	v_lshlrev_b32_e32 v134, 16, v135
	v_and_b32_e32 v135, 0xffff0000, v135
	v_pk_mul_f32 v[178:179], v[178:179], v[140:141]
	v_pk_mul_f32 v[180:181], v[180:181], v[142:143]
	v_pk_mul_f32 v[182:183], v[182:183], v[132:133]
	v_pk_mul_f32 v[184:185], v[184:185], v[134:135]
	v_pk_mul_f32 v[128:129], v[128:129], v[178:179]
	v_pk_mul_f32 v[130:131], v[130:131], v[180:181]
	v_pk_mul_f32 v[124:125], v[124:125], v[182:183]
	v_pk_mul_f32 v[126:127], v[126:127], v[184:185]
	v_lshlrev_b32_e32 v246, 16, v188
	v_and_b32_e32 v247, 0xffff0000, v188
	v_lshlrev_b32_e32 v248, 16, v189
	v_and_b32_e32 v249, 0xffff0000, v189
	v_lshlrev_b32_e32 v250, 16, v190
	v_and_b32_e32 v251, 0xffff0000, v190
	v_lshlrev_b32_e32 v252, 16, v191
	v_and_b32_e32 v253, 0xffff0000, v191
	v_rcp_f32_e32 v246, v246
	v_rcp_f32_e32 v247, v247
	v_rcp_f32_e32 v248, v248
	v_rcp_f32_e32 v249, v249
	v_rcp_f32_e32 v250, v250
	v_rcp_f32_e32 v251, v251
	v_rcp_f32_e32 v252, v252
	v_rcp_f32_e32 v253, v253
	v_lshlrev_b32_e32 v188, 16, v136
	v_and_b32_e32 v189, 0xffff0000, v136
	v_lshlrev_b32_e32 v190, 16, v137
	v_and_b32_e32 v191, 0xffff0000, v137
	v_lshlrev_b32_e32 v136, 16, v138
	v_and_b32_e32 v137, 0xffff0000, v138
	v_lshlrev_b32_e32 v138, 16, v139
	v_and_b32_e32 v139, 0xffff0000, v139
	v_pk_mul_f32 v[246:247], v[246:247], v[188:189]
	v_pk_mul_f32 v[248:249], v[248:249], v[190:191]
	v_pk_mul_f32 v[250:251], v[250:251], v[136:137]
	v_pk_mul_f32 v[252:253], v[252:253], v[138:139]
	v_pk_mul_f32 v[120:121], v[120:121], v[246:247]
	v_pk_mul_f32 v[122:123], v[122:123], v[248:249]
	v_pk_mul_f32 v[116:117], v[116:117], v[250:251]
	v_pk_mul_f32 v[118:119], v[118:119], v[252:253]
	global_load_dwordx4 v[132:135], v[2:3], off
	global_load_dwordx4 v[136:139], v[2:3], off offset:1024
	global_load_dwordx4 v[140:143], v[254:255], off
	global_load_dwordx4 v[188:191], v[254:255], off offset:1024
	v_lshl_add_u64 v[2:3], v[2:3], 0, s[20:21]
	v_lshl_add_u64 v[254:255], v[254:255], 0, s[20:21]
	s_waitcnt vmcnt(12)
	v_lshlrev_b32_e32 v178, 16, v200
	v_and_b32_e32 v179, 0xffff0000, v200
	v_lshlrev_b32_e32 v180, 16, v201
	v_and_b32_e32 v181, 0xffff0000, v201
	v_lshlrev_b32_e32 v182, 16, v202
	v_and_b32_e32 v183, 0xffff0000, v202
	v_lshlrev_b32_e32 v184, 16, v203
	v_and_b32_e32 v185, 0xffff0000, v203
	v_rcp_f32_e32 v178, v178
	v_rcp_f32_e32 v179, v179
	v_rcp_f32_e32 v180, v180
	v_rcp_f32_e32 v181, v181
	v_rcp_f32_e32 v182, v182
	v_rcp_f32_e32 v183, v183
	v_rcp_f32_e32 v184, v184
	v_rcp_f32_e32 v185, v185
	v_lshlrev_b32_e32 v200, 16, v192
	v_and_b32_e32 v201, 0xffff0000, v192
	v_lshlrev_b32_e32 v202, 16, v193
	v_and_b32_e32 v203, 0xffff0000, v193
	v_lshlrev_b32_e32 v192, 16, v194
	v_and_b32_e32 v193, 0xffff0000, v194
	v_lshlrev_b32_e32 v194, 16, v195
	v_and_b32_e32 v195, 0xffff0000, v195
	v_pk_mul_f32 v[178:179], v[178:179], v[200:201]
	v_pk_mul_f32 v[180:181], v[180:181], v[202:203]
	v_pk_mul_f32 v[182:183], v[182:183], v[192:193]
	v_pk_mul_f32 v[184:185], v[184:185], v[194:195]
	v_pk_mul_f32 v[112:113], v[112:113], v[178:179]
	v_pk_mul_f32 v[114:115], v[114:115], v[180:181]
	v_pk_mul_f32 v[108:109], v[108:109], v[182:183]
	v_pk_mul_f32 v[110:111], v[110:111], v[184:185]
	v_lshlrev_b32_e32 v246, 16, v204
	v_and_b32_e32 v247, 0xffff0000, v204
	v_lshlrev_b32_e32 v248, 16, v205
	v_and_b32_e32 v249, 0xffff0000, v205
	v_lshlrev_b32_e32 v250, 16, v206
	v_and_b32_e32 v251, 0xffff0000, v206
	v_lshlrev_b32_e32 v252, 16, v207
	v_and_b32_e32 v253, 0xffff0000, v207
	v_rcp_f32_e32 v246, v246
	v_rcp_f32_e32 v247, v247
	v_rcp_f32_e32 v248, v248
	v_rcp_f32_e32 v249, v249
	v_rcp_f32_e32 v250, v250
	v_rcp_f32_e32 v251, v251
	v_rcp_f32_e32 v252, v252
	v_rcp_f32_e32 v253, v253
	v_lshlrev_b32_e32 v204, 16, v196
	v_and_b32_e32 v205, 0xffff0000, v196
	v_lshlrev_b32_e32 v206, 16, v197
	v_and_b32_e32 v207, 0xffff0000, v197
	v_lshlrev_b32_e32 v196, 16, v198
	v_and_b32_e32 v197, 0xffff0000, v198
	v_lshlrev_b32_e32 v198, 16, v199
	v_and_b32_e32 v199, 0xffff0000, v199
	v_pk_mul_f32 v[246:247], v[246:247], v[204:205]
	v_pk_mul_f32 v[248:249], v[248:249], v[206:207]
	v_pk_mul_f32 v[250:251], v[250:251], v[196:197]
	v_pk_mul_f32 v[252:253], v[252:253], v[198:199]
	v_pk_mul_f32 v[104:105], v[104:105], v[246:247]
	v_pk_mul_f32 v[106:107], v[106:107], v[248:249]
	v_pk_mul_f32 v[100:101], v[100:101], v[250:251]
	v_pk_mul_f32 v[102:103], v[102:103], v[252:253]
	global_load_dwordx4 v[192:195], v[2:3], off
	global_load_dwordx4 v[196:199], v[2:3], off offset:1024
	global_load_dwordx4 v[200:203], v[254:255], off
	global_load_dwordx4 v[204:207], v[254:255], off offset:1024
	v_lshl_add_u64 v[2:3], v[2:3], 0, s[20:21]
	v_lshl_add_u64 v[254:255], v[254:255], 0, s[20:21]
	s_waitcnt vmcnt(12)
	v_lshlrev_b32_e32 v178, 16, v216
	v_and_b32_e32 v179, 0xffff0000, v216
	v_lshlrev_b32_e32 v180, 16, v217
	v_and_b32_e32 v181, 0xffff0000, v217
	v_lshlrev_b32_e32 v182, 16, v218
	v_and_b32_e32 v183, 0xffff0000, v218
	v_lshlrev_b32_e32 v184, 16, v219
	v_and_b32_e32 v185, 0xffff0000, v219
	v_rcp_f32_e32 v178, v178
	v_rcp_f32_e32 v179, v179
	v_rcp_f32_e32 v180, v180
	v_rcp_f32_e32 v181, v181
	v_rcp_f32_e32 v182, v182
	v_rcp_f32_e32 v183, v183
	v_rcp_f32_e32 v184, v184
	v_rcp_f32_e32 v185, v185
	v_lshlrev_b32_e32 v216, 16, v208
	v_and_b32_e32 v217, 0xffff0000, v208
	v_lshlrev_b32_e32 v218, 16, v209
	v_and_b32_e32 v219, 0xffff0000, v209
	v_lshlrev_b32_e32 v208, 16, v210
	v_and_b32_e32 v209, 0xffff0000, v210
	v_lshlrev_b32_e32 v210, 16, v211
	v_and_b32_e32 v211, 0xffff0000, v211
	v_pk_mul_f32 v[178:179], v[178:179], v[216:217]
	v_pk_mul_f32 v[180:181], v[180:181], v[218:219]
	v_pk_mul_f32 v[182:183], v[182:183], v[208:209]
	v_pk_mul_f32 v[184:185], v[184:185], v[210:211]
	v_pk_mul_f32 v[96:97], v[96:97], v[178:179]
	v_pk_mul_f32 v[98:99], v[98:99], v[180:181]
	v_pk_mul_f32 v[92:93], v[92:93], v[182:183]
	v_pk_mul_f32 v[94:95], v[94:95], v[184:185]
	v_lshlrev_b32_e32 v246, 16, v220
	v_and_b32_e32 v247, 0xffff0000, v220
	v_lshlrev_b32_e32 v248, 16, v221
	v_and_b32_e32 v249, 0xffff0000, v221
	v_lshlrev_b32_e32 v250, 16, v222
	v_and_b32_e32 v251, 0xffff0000, v222
	v_lshlrev_b32_e32 v252, 16, v223
	v_and_b32_e32 v253, 0xffff0000, v223
	v_rcp_f32_e32 v246, v246
	v_rcp_f32_e32 v247, v247
	v_rcp_f32_e32 v248, v248
	v_rcp_f32_e32 v249, v249
	v_rcp_f32_e32 v250, v250
	v_rcp_f32_e32 v251, v251
	v_rcp_f32_e32 v252, v252
	v_rcp_f32_e32 v253, v253
	v_lshlrev_b32_e32 v220, 16, v212
	v_and_b32_e32 v221, 0xffff0000, v212
	v_lshlrev_b32_e32 v222, 16, v213
	v_and_b32_e32 v223, 0xffff0000, v213
	v_lshlrev_b32_e32 v212, 16, v214
	v_and_b32_e32 v213, 0xffff0000, v214
	v_lshlrev_b32_e32 v214, 16, v215
	v_and_b32_e32 v215, 0xffff0000, v215
	v_pk_mul_f32 v[246:247], v[246:247], v[220:221]
	v_pk_mul_f32 v[248:249], v[248:249], v[222:223]
	v_pk_mul_f32 v[250:251], v[250:251], v[212:213]
	v_pk_mul_f32 v[252:253], v[252:253], v[214:215]
	v_pk_mul_f32 v[88:89], v[88:89], v[246:247]
	v_pk_mul_f32 v[90:91], v[90:91], v[248:249]
	v_pk_mul_f32 v[84:85], v[84:85], v[250:251]
	v_pk_mul_f32 v[86:87], v[86:87], v[252:253]
	global_load_dwordx4 v[208:211], v[2:3], off
	global_load_dwordx4 v[212:215], v[2:3], off offset:1024
	global_load_dwordx4 v[216:219], v[254:255], off
	global_load_dwordx4 v[220:223], v[254:255], off offset:1024
	v_lshl_add_u64 v[2:3], v[2:3], 0, s[20:21]
	v_lshl_add_u64 v[254:255], v[254:255], 0, s[20:21]
	s_waitcnt vmcnt(12)
	v_lshlrev_b32_e32 v178, 16, v232
	v_and_b32_e32 v179, 0xffff0000, v232
	v_lshlrev_b32_e32 v180, 16, v233
	v_and_b32_e32 v181, 0xffff0000, v233
	v_lshlrev_b32_e32 v182, 16, v234
	v_and_b32_e32 v183, 0xffff0000, v234
	v_lshlrev_b32_e32 v184, 16, v235
	v_and_b32_e32 v185, 0xffff0000, v235
	v_rcp_f32_e32 v178, v178
	v_rcp_f32_e32 v179, v179
	v_rcp_f32_e32 v180, v180
	v_rcp_f32_e32 v181, v181
	v_rcp_f32_e32 v182, v182
	v_rcp_f32_e32 v183, v183
	v_rcp_f32_e32 v184, v184
	v_rcp_f32_e32 v185, v185
	v_lshlrev_b32_e32 v232, 16, v224
	v_and_b32_e32 v233, 0xffff0000, v224
	v_lshlrev_b32_e32 v234, 16, v225
	v_and_b32_e32 v235, 0xffff0000, v225
	v_lshlrev_b32_e32 v224, 16, v226
	v_and_b32_e32 v225, 0xffff0000, v226
	v_lshlrev_b32_e32 v226, 16, v227
	v_and_b32_e32 v227, 0xffff0000, v227
	v_pk_mul_f32 v[178:179], v[178:179], v[232:233]
	v_pk_mul_f32 v[180:181], v[180:181], v[234:235]
	v_pk_mul_f32 v[182:183], v[182:183], v[224:225]
	v_pk_mul_f32 v[184:185], v[184:185], v[226:227]
	v_pk_mul_f32 v[80:81], v[80:81], v[178:179]
	v_pk_mul_f32 v[82:83], v[82:83], v[180:181]
	v_pk_mul_f32 v[76:77], v[76:77], v[182:183]
	v_pk_mul_f32 v[78:79], v[78:79], v[184:185]
	v_lshlrev_b32_e32 v246, 16, v236
	v_and_b32_e32 v247, 0xffff0000, v236
	v_lshlrev_b32_e32 v248, 16, v237
	v_and_b32_e32 v249, 0xffff0000, v237
	v_lshlrev_b32_e32 v250, 16, v238
	v_and_b32_e32 v251, 0xffff0000, v238
	v_lshlrev_b32_e32 v252, 16, v239
	v_and_b32_e32 v253, 0xffff0000, v239
	v_rcp_f32_e32 v246, v246
	v_rcp_f32_e32 v247, v247
	v_rcp_f32_e32 v248, v248
	v_rcp_f32_e32 v249, v249
	v_rcp_f32_e32 v250, v250
	v_rcp_f32_e32 v251, v251
	v_rcp_f32_e32 v252, v252
	v_rcp_f32_e32 v253, v253
	v_lshlrev_b32_e32 v236, 16, v228
	v_and_b32_e32 v237, 0xffff0000, v228
	v_lshlrev_b32_e32 v238, 16, v229
	v_and_b32_e32 v239, 0xffff0000, v229
	v_lshlrev_b32_e32 v228, 16, v230
	v_and_b32_e32 v229, 0xffff0000, v230
	v_lshlrev_b32_e32 v230, 16, v231
	v_and_b32_e32 v231, 0xffff0000, v231
	v_pk_mul_f32 v[246:247], v[246:247], v[236:237]
	v_pk_mul_f32 v[248:249], v[248:249], v[238:239]
	v_pk_mul_f32 v[250:251], v[250:251], v[228:229]
	v_pk_mul_f32 v[252:253], v[252:253], v[230:231]
	v_pk_mul_f32 v[72:73], v[72:73], v[246:247]
	v_pk_mul_f32 v[74:75], v[74:75], v[248:249]
	v_pk_mul_f32 v[68:69], v[68:69], v[250:251]
	v_pk_mul_f32 v[70:71], v[70:71], v[252:253]
	global_load_dwordx4 v[224:227], v[2:3], off
	global_load_dwordx4 v[228:231], v[2:3], off offset:1024
	global_load_dwordx4 v[232:235], v[254:255], off
	global_load_dwordx4 v[236:239], v[254:255], off offset:1024
	s_waitcnt vmcnt(12)
	v_lshlrev_b32_e32 v178, 16, v140
	v_and_b32_e32 v179, 0xffff0000, v140
	v_lshlrev_b32_e32 v180, 16, v141
	v_and_b32_e32 v181, 0xffff0000, v141
	v_lshlrev_b32_e32 v182, 16, v142
	v_and_b32_e32 v183, 0xffff0000, v142
	v_lshlrev_b32_e32 v184, 16, v143
	v_and_b32_e32 v185, 0xffff0000, v143
	v_rcp_f32_e32 v178, v178
	v_rcp_f32_e32 v179, v179
	v_rcp_f32_e32 v180, v180
	v_rcp_f32_e32 v181, v181
	v_rcp_f32_e32 v182, v182
	v_rcp_f32_e32 v183, v183
	v_rcp_f32_e32 v184, v184
	v_rcp_f32_e32 v185, v185
	v_lshlrev_b32_e32 v140, 16, v132
	v_and_b32_e32 v141, 0xffff0000, v132
	v_lshlrev_b32_e32 v142, 16, v133
	v_and_b32_e32 v143, 0xffff0000, v133
	v_lshlrev_b32_e32 v132, 16, v134
	v_and_b32_e32 v133, 0xffff0000, v134
	v_lshlrev_b32_e32 v134, 16, v135
	v_and_b32_e32 v135, 0xffff0000, v135
	v_pk_mul_f32 v[178:179], v[178:179], v[140:141]
	v_pk_mul_f32 v[180:181], v[180:181], v[142:143]
	v_pk_mul_f32 v[182:183], v[182:183], v[132:133]
	v_pk_mul_f32 v[184:185], v[184:185], v[134:135]
	v_pk_mul_f32 v[64:65], v[64:65], v[178:179]
	v_pk_mul_f32 v[66:67], v[66:67], v[180:181]
	v_pk_mul_f32 v[60:61], v[60:61], v[182:183]
	v_pk_mul_f32 v[62:63], v[62:63], v[184:185]
	v_lshlrev_b32_e32 v246, 16, v188
	v_and_b32_e32 v247, 0xffff0000, v188
	v_lshlrev_b32_e32 v248, 16, v189
	v_and_b32_e32 v249, 0xffff0000, v189
	v_lshlrev_b32_e32 v250, 16, v190
	v_and_b32_e32 v251, 0xffff0000, v190
	v_lshlrev_b32_e32 v252, 16, v191
	v_and_b32_e32 v253, 0xffff0000, v191
	v_rcp_f32_e32 v246, v246
	v_rcp_f32_e32 v247, v247
	v_rcp_f32_e32 v248, v248
	v_rcp_f32_e32 v249, v249
	v_rcp_f32_e32 v250, v250
	v_rcp_f32_e32 v251, v251
	v_rcp_f32_e32 v252, v252
	v_rcp_f32_e32 v253, v253
	v_lshlrev_b32_e32 v188, 16, v136
	v_and_b32_e32 v189, 0xffff0000, v136
	v_lshlrev_b32_e32 v190, 16, v137
	v_and_b32_e32 v191, 0xffff0000, v137
	v_lshlrev_b32_e32 v136, 16, v138
	v_and_b32_e32 v137, 0xffff0000, v138
	v_lshlrev_b32_e32 v138, 16, v139
	v_and_b32_e32 v139, 0xffff0000, v139
	v_pk_mul_f32 v[246:247], v[246:247], v[188:189]
	v_pk_mul_f32 v[248:249], v[248:249], v[190:191]
	v_pk_mul_f32 v[250:251], v[250:251], v[136:137]
	v_pk_mul_f32 v[252:253], v[252:253], v[138:139]
	v_pk_mul_f32 v[56:57], v[56:57], v[246:247]
	v_pk_mul_f32 v[58:59], v[58:59], v[248:249]
	v_pk_mul_f32 v[52:53], v[52:53], v[250:251]
	v_pk_mul_f32 v[54:55], v[54:55], v[252:253]
	s_waitcnt vmcnt(8)
	v_lshlrev_b32_e32 v178, 16, v200
	v_and_b32_e32 v179, 0xffff0000, v200
	v_lshlrev_b32_e32 v180, 16, v201
	v_and_b32_e32 v181, 0xffff0000, v201
	v_lshlrev_b32_e32 v182, 16, v202
	v_and_b32_e32 v183, 0xffff0000, v202
	v_lshlrev_b32_e32 v184, 16, v203
	v_and_b32_e32 v185, 0xffff0000, v203
	v_rcp_f32_e32 v178, v178
	v_rcp_f32_e32 v179, v179
	v_rcp_f32_e32 v180, v180
	v_rcp_f32_e32 v181, v181
	v_rcp_f32_e32 v182, v182
	v_rcp_f32_e32 v183, v183
	v_rcp_f32_e32 v184, v184
	v_rcp_f32_e32 v185, v185
	v_lshlrev_b32_e32 v200, 16, v192
	v_and_b32_e32 v201, 0xffff0000, v192
	v_lshlrev_b32_e32 v202, 16, v193
	v_and_b32_e32 v203, 0xffff0000, v193
	v_lshlrev_b32_e32 v192, 16, v194
	v_and_b32_e32 v193, 0xffff0000, v194
	v_lshlrev_b32_e32 v194, 16, v195
	v_and_b32_e32 v195, 0xffff0000, v195
	v_pk_mul_f32 v[178:179], v[178:179], v[200:201]
	v_pk_mul_f32 v[180:181], v[180:181], v[202:203]
	v_pk_mul_f32 v[182:183], v[182:183], v[192:193]
	v_pk_mul_f32 v[184:185], v[184:185], v[194:195]
	v_pk_mul_f32 v[48:49], v[48:49], v[178:179]
	v_pk_mul_f32 v[50:51], v[50:51], v[180:181]
	v_pk_mul_f32 v[44:45], v[44:45], v[182:183]
	v_pk_mul_f32 v[46:47], v[46:47], v[184:185]
	v_lshlrev_b32_e32 v246, 16, v204
	v_and_b32_e32 v247, 0xffff0000, v204
	v_lshlrev_b32_e32 v248, 16, v205
	v_and_b32_e32 v249, 0xffff0000, v205
	v_lshlrev_b32_e32 v250, 16, v206
	v_and_b32_e32 v251, 0xffff0000, v206
	v_lshlrev_b32_e32 v252, 16, v207
	v_and_b32_e32 v253, 0xffff0000, v207
	v_rcp_f32_e32 v246, v246
	v_rcp_f32_e32 v247, v247
	v_rcp_f32_e32 v248, v248
	v_rcp_f32_e32 v249, v249
	v_rcp_f32_e32 v250, v250
	v_rcp_f32_e32 v251, v251
	v_rcp_f32_e32 v252, v252
	v_rcp_f32_e32 v253, v253
	v_lshlrev_b32_e32 v204, 16, v196
	v_and_b32_e32 v205, 0xffff0000, v196
	v_lshlrev_b32_e32 v206, 16, v197
	v_and_b32_e32 v207, 0xffff0000, v197
	v_lshlrev_b32_e32 v196, 16, v198
	v_and_b32_e32 v197, 0xffff0000, v198
	v_lshlrev_b32_e32 v198, 16, v199
	v_and_b32_e32 v199, 0xffff0000, v199
	v_pk_mul_f32 v[246:247], v[246:247], v[204:205]
	v_pk_mul_f32 v[248:249], v[248:249], v[206:207]
	v_pk_mul_f32 v[250:251], v[250:251], v[196:197]
	v_pk_mul_f32 v[252:253], v[252:253], v[198:199]
	v_pk_mul_f32 v[40:41], v[40:41], v[246:247]
	v_pk_mul_f32 v[42:43], v[42:43], v[248:249]
	v_pk_mul_f32 v[36:37], v[36:37], v[250:251]
	v_pk_mul_f32 v[38:39], v[38:39], v[252:253]
	s_waitcnt vmcnt(4)
	v_lshlrev_b32_e32 v178, 16, v216
	v_and_b32_e32 v179, 0xffff0000, v216
	v_lshlrev_b32_e32 v180, 16, v217
	v_and_b32_e32 v181, 0xffff0000, v217
	v_lshlrev_b32_e32 v182, 16, v218
	v_and_b32_e32 v183, 0xffff0000, v218
	v_lshlrev_b32_e32 v184, 16, v219
	v_and_b32_e32 v185, 0xffff0000, v219
	v_rcp_f32_e32 v178, v178
	v_rcp_f32_e32 v179, v179
	v_rcp_f32_e32 v180, v180
	v_rcp_f32_e32 v181, v181
	v_rcp_f32_e32 v182, v182
	v_rcp_f32_e32 v183, v183
	v_rcp_f32_e32 v184, v184
	v_rcp_f32_e32 v185, v185
	v_lshlrev_b32_e32 v216, 16, v208
	v_and_b32_e32 v217, 0xffff0000, v208
	v_lshlrev_b32_e32 v218, 16, v209
	v_and_b32_e32 v219, 0xffff0000, v209
	v_lshlrev_b32_e32 v208, 16, v210
	v_and_b32_e32 v209, 0xffff0000, v210
	v_lshlrev_b32_e32 v210, 16, v211
	v_and_b32_e32 v211, 0xffff0000, v211
	v_pk_mul_f32 v[178:179], v[178:179], v[216:217]
	v_pk_mul_f32 v[180:181], v[180:181], v[218:219]
	v_pk_mul_f32 v[182:183], v[182:183], v[208:209]
	v_pk_mul_f32 v[184:185], v[184:185], v[210:211]
	v_pk_mul_f32 v[32:33], v[32:33], v[178:179]
	v_pk_mul_f32 v[34:35], v[34:35], v[180:181]
	v_pk_mul_f32 v[28:29], v[28:29], v[182:183]
	v_pk_mul_f32 v[30:31], v[30:31], v[184:185]
	v_lshlrev_b32_e32 v246, 16, v220
	v_and_b32_e32 v247, 0xffff0000, v220
	v_lshlrev_b32_e32 v248, 16, v221
	v_and_b32_e32 v249, 0xffff0000, v221
	v_lshlrev_b32_e32 v250, 16, v222
	v_and_b32_e32 v251, 0xffff0000, v222
	v_lshlrev_b32_e32 v252, 16, v223
	v_and_b32_e32 v253, 0xffff0000, v223
	v_rcp_f32_e32 v246, v246
	v_rcp_f32_e32 v247, v247
	v_rcp_f32_e32 v248, v248
	v_rcp_f32_e32 v249, v249
	v_rcp_f32_e32 v250, v250
	v_rcp_f32_e32 v251, v251
	v_rcp_f32_e32 v252, v252
	v_rcp_f32_e32 v253, v253
	v_lshlrev_b32_e32 v220, 16, v212
	v_and_b32_e32 v221, 0xffff0000, v212
	v_lshlrev_b32_e32 v222, 16, v213
	v_and_b32_e32 v223, 0xffff0000, v213
	v_lshlrev_b32_e32 v212, 16, v214
	v_and_b32_e32 v213, 0xffff0000, v214
	v_lshlrev_b32_e32 v214, 16, v215
	v_and_b32_e32 v215, 0xffff0000, v215
	v_pk_mul_f32 v[246:247], v[246:247], v[220:221]
	v_pk_mul_f32 v[248:249], v[248:249], v[222:223]
	v_pk_mul_f32 v[250:251], v[250:251], v[212:213]
	v_pk_mul_f32 v[252:253], v[252:253], v[214:215]
	v_pk_mul_f32 v[24:25], v[24:25], v[246:247]
	v_pk_mul_f32 v[26:27], v[26:27], v[248:249]
	v_pk_mul_f32 v[20:21], v[20:21], v[250:251]
	v_pk_mul_f32 v[22:23], v[22:23], v[252:253]
	s_waitcnt vmcnt(0)
	v_lshlrev_b32_e32 v178, 16, v232
	v_and_b32_e32 v179, 0xffff0000, v232
	v_lshlrev_b32_e32 v180, 16, v233
	v_and_b32_e32 v181, 0xffff0000, v233
	v_lshlrev_b32_e32 v182, 16, v234
	v_and_b32_e32 v183, 0xffff0000, v234
	v_lshlrev_b32_e32 v184, 16, v235
	v_and_b32_e32 v185, 0xffff0000, v235
	v_rcp_f32_e32 v178, v178
	v_rcp_f32_e32 v179, v179
	v_rcp_f32_e32 v180, v180
	v_rcp_f32_e32 v181, v181
	v_rcp_f32_e32 v182, v182
	v_rcp_f32_e32 v183, v183
	v_rcp_f32_e32 v184, v184
	v_rcp_f32_e32 v185, v185
	v_lshlrev_b32_e32 v232, 16, v224
	v_and_b32_e32 v233, 0xffff0000, v224
	v_lshlrev_b32_e32 v234, 16, v225
	v_and_b32_e32 v235, 0xffff0000, v225
	v_lshlrev_b32_e32 v224, 16, v226
	v_and_b32_e32 v225, 0xffff0000, v226
	v_lshlrev_b32_e32 v226, 16, v227
	v_and_b32_e32 v227, 0xffff0000, v227
	v_pk_mul_f32 v[178:179], v[178:179], v[232:233]
	v_pk_mul_f32 v[180:181], v[180:181], v[234:235]
	v_pk_mul_f32 v[182:183], v[182:183], v[224:225]
	v_pk_mul_f32 v[184:185], v[184:185], v[226:227]
	v_pk_mul_f32 v[16:17], v[16:17], v[178:179]
	v_pk_mul_f32 v[18:19], v[18:19], v[180:181]
	v_pk_mul_f32 v[12:13], v[12:13], v[182:183]
	v_pk_mul_f32 v[14:15], v[14:15], v[184:185]
	v_lshlrev_b32_e32 v246, 16, v236
	v_and_b32_e32 v247, 0xffff0000, v236
	v_lshlrev_b32_e32 v248, 16, v237
	v_and_b32_e32 v249, 0xffff0000, v237
	v_lshlrev_b32_e32 v250, 16, v238
	v_and_b32_e32 v251, 0xffff0000, v238
	v_lshlrev_b32_e32 v252, 16, v239
	v_and_b32_e32 v253, 0xffff0000, v239
	v_rcp_f32_e32 v246, v246
	v_rcp_f32_e32 v247, v247
	v_rcp_f32_e32 v248, v248
	v_rcp_f32_e32 v249, v249
	v_rcp_f32_e32 v250, v250
	v_rcp_f32_e32 v251, v251
	v_rcp_f32_e32 v252, v252
	v_rcp_f32_e32 v253, v253
	v_lshlrev_b32_e32 v236, 16, v228
	v_and_b32_e32 v237, 0xffff0000, v228
	v_lshlrev_b32_e32 v238, 16, v229
	v_and_b32_e32 v239, 0xffff0000, v229
	v_lshlrev_b32_e32 v228, 16, v230
	v_and_b32_e32 v229, 0xffff0000, v230
	v_lshlrev_b32_e32 v230, 16, v231
	v_and_b32_e32 v231, 0xffff0000, v231
	v_pk_mul_f32 v[246:247], v[246:247], v[236:237]
	v_pk_mul_f32 v[248:249], v[248:249], v[238:239]
	v_pk_mul_f32 v[250:251], v[250:251], v[228:229]
	v_pk_mul_f32 v[252:253], v[252:253], v[230:231]
	v_pk_mul_f32 v[8:9], v[8:9], v[246:247]
	v_pk_mul_f32 v[10:11], v[10:11], v[248:249]
	v_pk_mul_f32 v[4:5], v[4:5], v[250:251]
	v_pk_mul_f32 v[6:7], v[6:7], v[252:253]

.Lpeel_mid_p3:
	s_add_i32 s75, 0, 0x18000
	v_add_u32_e32 v1, s75, v173
	s_add_i32 s91, 0, 0x1c000
	ds_read_b128 v[132:135], v1
	ds_read_b128 v[136:139], v1 offset:1024
	ds_read_b128 v[140:143], v1 offset:2048
	ds_read_b128 v[178:181], v1 offset:3072
	v_add_u32_e32 v1, s91, v173
	ds_read_b128 v[182:185], v1
	ds_read_b128 v[188:191], v1 offset:1024
	ds_read_b128 v[192:195], v1 offset:2048
	ds_read_b128 v[196:199], v1 offset:3072
	s_add_u32 s66, s66, 0xa0000
	s_addc_u32 s67, s67, 0
	s_mov_b32 m0, s71
	v_lshl_add_u64 v[6:7], s[66:67], 0, v[150:151]
	ds_read_b128 v[200:203], v174 offset:32768
	ds_read_b128 v[204:207], v174 offset:33792
	ds_read_b128 v[208:211], v174 offset:34816
	ds_read_b128 v[212:215], v174 offset:35840
	ds_read_b128 v[216:219], v174 offset:36864
	ds_read_b128 v[220:223], v174 offset:37888
	ds_read_b128 v[224:227], v174 offset:38912
	ds_read_b128 v[228:231], v174 offset:39936
	global_load_lds_dwordx4 v[6:7], off
	v_lshl_add_u64 v[6:7], s[66:67], 0, v[146:147]
	s_mov_b32 m0, s72
	s_nop 0
	global_load_lds_dwordx4 v[6:7], off
	s_waitcnt vmcnt(8)
	s_waitcnt lgkmcnt(0)
	s_waitcnt lgkmcnt(0)
	s_setprio 1
	s_barrier
	v_mfma_f32_16x16x32_bf16 v[128:131], v[132:135], v[200:203], v[128:131]
	v_mfma_f32_16x16x32_bf16 v[124:127], v[140:143], v[200:203], v[124:127]
	v_mfma_f32_16x16x32_bf16 v[112:115], v[132:135], v[208:211], v[112:115]
	v_mfma_f32_16x16x32_bf16 v[108:111], v[140:143], v[208:211], v[108:111]
	v_mfma_f32_16x16x32_bf16 v[96:99], v[132:135], v[216:219], v[96:99]
	v_mfma_f32_16x16x32_bf16 v[92:95], v[140:143], v[216:219], v[92:95]
	v_mfma_f32_16x16x32_bf16 v[80:83], v[132:135], v[224:227], v[80:83]
	v_mfma_f32_16x16x32_bf16 v[76:79], v[140:143], v[224:227], v[76:79]
	v_mfma_f32_16x16x32_bf16 v[128:131], v[136:139], v[204:207], v[128:131]
	v_mfma_f32_16x16x32_bf16 v[124:127], v[178:181], v[204:207], v[124:127]
	v_mfma_f32_16x16x32_bf16 v[112:115], v[136:139], v[212:215], v[112:115]
	v_mfma_f32_16x16x32_bf16 v[108:111], v[178:181], v[212:215], v[108:111]
	v_mfma_f32_16x16x32_bf16 v[96:99], v[136:139], v[220:223], v[96:99]
	v_mfma_f32_16x16x32_bf16 v[92:95], v[178:181], v[220:223], v[92:95]
	v_mfma_f32_16x16x32_bf16 v[80:83], v[136:139], v[228:231], v[80:83]
	v_mfma_f32_16x16x32_bf16 v[76:79], v[178:181], v[228:231], v[76:79]
	s_setprio 0
	s_setprio 1
	v_mfma_f32_16x16x32_bf16 v[120:123], v[182:185], v[200:203], v[120:123]
	v_mfma_f32_16x16x32_bf16 v[116:119], v[192:195], v[200:203], v[116:119]
	v_mfma_f32_16x16x32_bf16 v[104:107], v[182:185], v[208:211], v[104:107]
	v_mfma_f32_16x16x32_bf16 v[100:103], v[192:195], v[208:211], v[100:103]
	v_mfma_f32_16x16x32_bf16 v[88:91], v[182:185], v[216:219], v[88:91]
	v_mfma_f32_16x16x32_bf16 v[84:87], v[192:195], v[216:219], v[84:87]
	v_mfma_f32_16x16x32_bf16 v[72:75], v[182:185], v[224:227], v[72:75]
	v_mfma_f32_16x16x32_bf16 v[68:71], v[192:195], v[224:227], v[68:71]
	v_mfma_f32_16x16x32_bf16 v[120:123], v[188:191], v[204:207], v[120:123]
	v_mfma_f32_16x16x32_bf16 v[116:119], v[196:199], v[204:207], v[116:119]
	v_mfma_f32_16x16x32_bf16 v[104:107], v[188:191], v[212:215], v[104:107]
	v_mfma_f32_16x16x32_bf16 v[100:103], v[196:199], v[212:215], v[100:103]
	v_mfma_f32_16x16x32_bf16 v[88:91], v[188:191], v[220:223], v[88:91]
	v_mfma_f32_16x16x32_bf16 v[84:87], v[196:199], v[220:223], v[84:87]
	v_mfma_f32_16x16x32_bf16 v[72:75], v[188:191], v[228:231], v[72:75]
	v_mfma_f32_16x16x32_bf16 v[68:71], v[196:199], v[228:231], v[68:71]
	s_barrier
	s_setprio 0
	s_add_i32 s66, s75, s68
	v_lshl_add_u64 v[6:7], v[232:233], 0, s[14:15]
	s_mov_b32 m0, s66
	ds_read_b128 v[200:203], v174 offset:49152
	ds_read_b128 v[204:207], v174 offset:50176
	ds_read_b128 v[208:211], v174 offset:51200
	ds_read_b128 v[212:215], v174 offset:52224
	ds_read_b128 v[216:219], v174 offset:53248
	ds_read_b128 v[220:223], v174 offset:54272
	ds_read_b128 v[224:227], v174 offset:55296
	ds_read_b128 v[228:231], v174 offset:56320
	global_load_lds_dwordx4 v[6:7], off
	s_add_i32 m0, s66, 0x2000
	s_add_u32 s64, s64, 0xa0080
	v_lshl_add_u64 v[6:7], v[234:235], 0, s[14:15]
	s_addc_u32 s65, s65, 0
	s_add_i32 s66, s91, s68
	global_load_lds_dwordx4 v[6:7], off
	v_lshl_add_u64 v[6:7], s[64:65], 0, v[148:149]
	s_mov_b32 m0, s66
	s_nop 0
	global_load_lds_dwordx4 v[6:7], off
	v_lshl_add_u64 v[6:7], s[64:65], 0, v[144:145]
	s_add_i32 m0, s66, 0x2000
	s_nop 0
	global_load_lds_dwordx4 v[6:7], off
	v_lshl_add_u64 v[6:7], v[236:237], 0, s[14:15]
	s_mov_b32 m0, s73
	s_nop 0
	global_load_lds_dwordx4 v[6:7], off
	v_lshl_add_u64 v[6:7], v[238:239], 0, s[14:15]
	s_mov_b32 m0, s76
	s_nop 0
	global_load_lds_dwordx4 v[6:7], off
	s_waitcnt vmcnt(8)
	s_waitcnt lgkmcnt(0)
	s_waitcnt lgkmcnt(0)
	s_setprio 1
	s_barrier
	v_mfma_f32_16x16x32_bf16 v[64:67], v[132:135], v[200:203], v[64:67]
	v_mfma_f32_16x16x32_bf16 v[60:63], v[140:143], v[200:203], v[60:63]
	v_mfma_f32_16x16x32_bf16 v[48:51], v[132:135], v[208:211], v[48:51]
	v_mfma_f32_16x16x32_bf16 v[44:47], v[140:143], v[208:211], v[44:47]
	v_mfma_f32_16x16x32_bf16 v[32:35], v[132:135], v[216:219], v[32:35]
	v_mfma_f32_16x16x32_bf16 v[28:31], v[140:143], v[216:219], v[28:31]
	v_mfma_f32_16x16x32_bf16 v[16:19], v[132:135], v[224:227], v[16:19]
	v_mfma_f32_16x16x32_bf16 v[12:15], v[140:143], v[224:227], v[12:15]
	v_mfma_f32_16x16x32_bf16 v[64:67], v[136:139], v[204:207], v[64:67]
	v_mfma_f32_16x16x32_bf16 v[60:63], v[178:181], v[204:207], v[60:63]
	v_mfma_f32_16x16x32_bf16 v[48:51], v[136:139], v[212:215], v[48:51]
	s_add_u32 s60, s60, 0x100
	v_mfma_f32_16x16x32_bf16 v[44:47], v[178:181], v[212:215], v[44:47]
	s_addc_u32 s61, s61, 0
	v_mfma_f32_16x16x32_bf16 v[32:35], v[136:139], v[220:223], v[32:35]
	s_cmp_eq_u32 s2, 16
	v_mfma_f32_16x16x32_bf16 v[28:31], v[178:181], v[220:223], v[28:31]
	s_cselect_b32 s100, 1, 0
	v_mfma_f32_16x16x32_bf16 v[16:19], v[136:139], v[228:231], v[16:19]
	s_cmp_eq_u32 s2, 24
	v_mfma_f32_16x16x32_bf16 v[12:15], v[178:181], v[228:231], v[12:15]
	s_cselect_b32 s101, 1, 0
	s_setprio 0
	s_setprio 1
	v_mfma_f32_16x16x32_bf16 v[56:59], v[182:185], v[200:203], v[56:59]
	s_or_b32 s100, s100, s101
	v_mfma_f32_16x16x32_bf16 v[52:55], v[192:195], v[200:203], v[52:55]
	s_cmp_eq_u64 s[62:63], 0
	v_mfma_f32_16x16x32_bf16 v[40:43], v[182:185], v[208:211], v[40:43]
	s_cselect_b32 s100, s100, 0
	v_mfma_f32_16x16x32_bf16 v[36:39], v[192:195], v[208:211], v[36:39]
	s_cmp_ge_i32 s2, s88
	v_mfma_f32_16x16x32_bf16 v[24:27], v[182:185], v[216:219], v[24:27]
	s_cselect_b32 s67, 1, 0
	v_mfma_f32_16x16x32_bf16 v[20:23], v[192:195], v[216:219], v[20:23]
	s_cmp_eq_u64 s[18:19], 0
	v_mfma_f32_16x16x32_bf16 v[6:9], v[182:185], v[224:227], v[8:11]
	s_cselect_b32 s66, 0, s100
	v_mfma_f32_16x16x32_bf16 v[2:5], v[192:195], v[224:227], v[2:5]
	s_cselect_b32 s100, s100, 0
	v_mfma_f32_16x16x32_bf16 v[56:59], v[188:191], v[204:207], v[56:59]
	s_or_b32 s66, s66, s67
	v_mfma_f32_16x16x32_bf16 v[52:55], v[196:199], v[204:207], v[52:55]
	s_mov_b32 s64, s2
	v_mfma_f32_16x16x32_bf16 v[40:43], v[188:191], v[212:215], v[40:43]
	s_cmp_lg_u32 s100, 0
	v_mfma_f32_16x16x32_bf16 v[36:39], v[196:199], v[212:215], v[36:39]
	v_mfma_f32_16x16x32_bf16 v[24:27], v[188:191], v[220:223], v[24:27]
	v_mfma_f32_16x16x32_bf16 v[20:23], v[196:199], v[220:223], v[20:23]
	v_mfma_f32_16x16x32_bf16 v[8:11], v[188:191], v[228:231], v[6:9]
	v_mfma_f32_16x16x32_bf16 v[4:7], v[196:199], v[228:231], v[2:5]
	s_setprio 0
	s_cbranch_scc0 .Lhk_skipB

.Lhk_skipB:
	s_barrier
	s_cmp_lg_u32 s66, 0
	s_cbranch_scc1 .Lp3_special
	s_branch .LBB0_599
.Lp3_special:
	s_cmp_lg_u32 s67, 0
	s_cbranch_scc1 .LBB0_601
	s_branch .Lhook_top

.LBB0_671:
	s_add_u32 s6, s6, 0x80080
	s_addc_u32 s7, s7, 0
	s_add_u32 s5, s40, 0x100
	s_addc_u32 s25, s41, 0
	s_mov_b32 s56, -2
	ds_read_b128 v[128:131], v185
	ds_read_b128 v[132:135], v185 offset:1024
	ds_read_b128 v[136:139], v185 offset:2048
	ds_read_b128 v[140:143], v185 offset:3072
	ds_read_b128 v[162:165], v186
	ds_read_b128 v[166:169], v186 offset:1024
	ds_read_b128 v[170:173], v186 offset:2048
	ds_read_b128 v[174:177], v186 offset:3072
	s_add_u32 s38, s6, 0xfff80080
	s_addc_u32 s39, s7, -1
	s_cmp_eq_u32 s56, 28
	s_cselect_b32 s41, s27, s39
	s_cselect_b32 s40, s26, s38
	s_cselect_b32 s39, s23, s25
	s_cselect_b32 s38, s22, s5
	v_lshl_add_u64 v[182:183], s[6:7], 0, v[158:159]
	s_add_i32 m0, s42, 0xc000
	ds_read_b128 v[178:181], v188
	ds_read_b128 v[192:195], v188 offset:1024
	ds_read_b128 v[196:199], v188 offset:2048
	ds_read_b128 v[200:203], v188 offset:3072
	ds_read_b128 v[204:207], v188 offset:4096
	ds_read_b128 v[208:211], v188 offset:5120
	ds_read_b128 v[212:215], v188 offset:6144
	ds_read_b128 v[216:219], v188 offset:7168
	global_load_lds_dwordx4 v[182:183], off
	v_lshl_add_u64 v[182:183], s[6:7], 0, v[160:161]
	s_add_i32 m0, s42, 0xe000
	s_nop 0
	global_load_lds_dwordx4 v[182:183], off
	s_waitcnt vmcnt(8)
	s_waitcnt lgkmcnt(0)
	s_waitcnt lgkmcnt(0)
	s_setprio 1
	s_barrier
	v_mfma_f32_16x16x32_bf16 v[124:127], v[128:131], v[178:181], 0
	v_mfma_f32_16x16x32_bf16 v[120:123], v[136:139], v[178:181], 0
	v_mfma_f32_16x16x32_bf16 v[108:111], v[128:131], v[196:199], 0
	v_mfma_f32_16x16x32_bf16 v[104:107], v[136:139], v[196:199], 0
	v_mfma_f32_16x16x32_bf16 v[92:95], v[128:131], v[204:207], 0
	v_mfma_f32_16x16x32_bf16 v[88:91], v[136:139], v[204:207], 0
	v_mfma_f32_16x16x32_bf16 v[76:79], v[128:131], v[212:215], 0
	v_mfma_f32_16x16x32_bf16 v[72:75], v[136:139], v[212:215], 0
	v_mfma_f32_16x16x32_bf16 v[124:127], v[132:135], v[192:195], v[124:127]
	v_mfma_f32_16x16x32_bf16 v[120:123], v[140:143], v[192:195], v[120:123]
	v_mfma_f32_16x16x32_bf16 v[108:111], v[132:135], v[200:203], v[108:111]
	v_mfma_f32_16x16x32_bf16 v[104:107], v[140:143], v[200:203], v[104:107]
	v_mfma_f32_16x16x32_bf16 v[92:95], v[132:135], v[208:211], v[92:95]
	v_mfma_f32_16x16x32_bf16 v[88:91], v[140:143], v[208:211], v[88:91]
	v_mfma_f32_16x16x32_bf16 v[76:79], v[132:135], v[216:219], v[76:79]
	v_mfma_f32_16x16x32_bf16 v[72:75], v[140:143], v[216:219], v[72:75]
	s_setprio 0
	s_setprio 1
	v_mfma_f32_16x16x32_bf16 v[116:119], v[162:165], v[178:181], 0
	v_mfma_f32_16x16x32_bf16 v[112:115], v[170:173], v[178:181], 0
	v_mfma_f32_16x16x32_bf16 v[100:103], v[162:165], v[196:199], 0
	v_mfma_f32_16x16x32_bf16 v[96:99], v[170:173], v[196:199], 0
	v_mfma_f32_16x16x32_bf16 v[84:87], v[162:165], v[204:207], 0
	v_mfma_f32_16x16x32_bf16 v[80:83], v[170:173], v[204:207], 0
	v_mfma_f32_16x16x32_bf16 v[68:71], v[162:165], v[212:215], 0
	v_mfma_f32_16x16x32_bf16 v[64:67], v[170:173], v[212:215], 0
	v_mfma_f32_16x16x32_bf16 v[116:119], v[166:169], v[192:195], v[116:119]
	v_mfma_f32_16x16x32_bf16 v[112:115], v[174:177], v[192:195], v[112:115]
	v_mfma_f32_16x16x32_bf16 v[100:103], v[166:169], v[200:203], v[100:103]
	v_mfma_f32_16x16x32_bf16 v[96:99], v[174:177], v[200:203], v[96:99]
	v_mfma_f32_16x16x32_bf16 v[84:87], v[166:169], v[208:211], v[84:87]
	v_mfma_f32_16x16x32_bf16 v[80:83], v[174:177], v[208:211], v[80:83]
	v_mfma_f32_16x16x32_bf16 v[68:71], v[166:169], v[216:219], v[68:71]
	v_mfma_f32_16x16x32_bf16 v[64:67], v[174:177], v[216:219], v[64:67]
	s_barrier
	s_setprio 0
	s_add_i32 s57, s51, s35
	v_lshl_add_u64 v[182:183], s[38:39], 0, v[148:149]
	s_mov_b32 m0, s57
	ds_read_b128 v[178:181], v188 offset:16384
	ds_read_b128 v[192:195], v188 offset:17408
	ds_read_b128 v[196:199], v188 offset:18432
	ds_read_b128 v[200:203], v188 offset:19456
	ds_read_b128 v[204:207], v188 offset:20480
	ds_read_b128 v[208:211], v188 offset:21504
	ds_read_b128 v[212:215], v188 offset:22528
	ds_read_b128 v[216:219], v188 offset:23552
	global_load_lds_dwordx4 v[182:183], off
	s_add_i32 m0, s57, 0x2000
	s_add_u32 s58, s38, 0x80000
	v_lshl_add_u64 v[220:221], s[38:39], 0, v[144:145]
	s_addc_u32 s59, s39, 0
	s_add_i32 s57, s52, s35
	global_load_lds_dwordx4 v[220:221], off
	v_lshl_add_u64 v[222:223], s[58:59], 0, v[148:149]
	s_mov_b32 m0, s57
	v_lshl_add_u64 v[224:225], s[40:41], 0, v[146:147]
	global_load_lds_dwordx4 v[222:223], off
	v_lshl_add_u64 v[222:223], s[58:59], 0, v[144:145]
	s_add_i32 m0, s57, 0x2000
	s_nop 0
	global_load_lds_dwordx4 v[222:223], off
	v_lshl_add_u64 v[222:223], s[40:41], 0, v[150:151]
	s_mov_b32 m0, s42
	s_nop 0
	global_load_lds_dwordx4 v[222:223], off
	s_mov_b32 m0, s43
	s_nop 0
	global_load_lds_dwordx4 v[224:225], off
	s_waitcnt vmcnt(8)
	s_waitcnt lgkmcnt(0)
	s_waitcnt lgkmcnt(0)
	s_setprio 1
	s_barrier
	v_mfma_f32_16x16x32_bf16 v[60:63], v[128:131], v[178:181], 0
	v_mfma_f32_16x16x32_bf16 v[56:59], v[136:139], v[178:181], 0
	v_mfma_f32_16x16x32_bf16 v[44:47], v[128:131], v[196:199], 0
	v_mfma_f32_16x16x32_bf16 v[40:43], v[136:139], v[196:199], 0
	v_mfma_f32_16x16x32_bf16 v[28:31], v[128:131], v[204:207], 0
	v_mfma_f32_16x16x32_bf16 v[24:27], v[136:139], v[204:207], 0
	v_mfma_f32_16x16x32_bf16 v[12:15], v[128:131], v[212:215], 0
	v_mfma_f32_16x16x32_bf16 v[8:11], v[136:139], v[212:215], 0
	v_mfma_f32_16x16x32_bf16 v[60:63], v[132:135], v[192:195], v[60:63]
	v_mfma_f32_16x16x32_bf16 v[56:59], v[140:143], v[192:195], v[56:59]
	v_mfma_f32_16x16x32_bf16 v[44:47], v[132:135], v[200:203], v[44:47]
	v_mfma_f32_16x16x32_bf16 v[40:43], v[140:143], v[200:203], v[40:43]
	v_mfma_f32_16x16x32_bf16 v[28:31], v[132:135], v[208:211], v[28:31]
	v_mfma_f32_16x16x32_bf16 v[24:27], v[140:143], v[208:211], v[24:27]
	v_mfma_f32_16x16x32_bf16 v[12:15], v[132:135], v[216:219], v[12:15]
	v_mfma_f32_16x16x32_bf16 v[8:11], v[140:143], v[216:219], v[8:11]
	s_setprio 0
	s_setprio 1
	v_mfma_f32_16x16x32_bf16 v[52:55], v[162:165], v[178:181], 0
	v_mfma_f32_16x16x32_bf16 v[48:51], v[170:173], v[178:181], 0
	v_mfma_f32_16x16x32_bf16 v[36:39], v[162:165], v[196:199], 0
	v_mfma_f32_16x16x32_bf16 v[32:35], v[170:173], v[196:199], 0
	v_mfma_f32_16x16x32_bf16 v[20:23], v[162:165], v[204:207], 0
	v_mfma_f32_16x16x32_bf16 v[16:19], v[170:173], v[204:207], 0
	v_mfma_f32_16x16x32_bf16 v[4:7], v[162:165], v[212:215], 0
	v_mfma_f32_16x16x32_bf16 v[0:3], v[170:173], v[212:215], 0
	v_mfma_f32_16x16x32_bf16 v[52:55], v[166:169], v[192:195], v[52:55]
	v_mfma_f32_16x16x32_bf16 v[48:51], v[174:177], v[192:195], v[48:51]
	v_mfma_f32_16x16x32_bf16 v[36:39], v[166:169], v[200:203], v[36:39]
	v_mfma_f32_16x16x32_bf16 v[32:35], v[174:177], v[200:203], v[32:35]
	v_mfma_f32_16x16x32_bf16 v[20:23], v[166:169], v[208:211], v[20:23]
	v_mfma_f32_16x16x32_bf16 v[16:19], v[174:177], v[208:211], v[16:19]
	v_mfma_f32_16x16x32_bf16 v[4:7], v[166:169], v[216:219], v[4:7]
	v_mfma_f32_16x16x32_bf16 v[0:3], v[174:177], v[216:219], v[0:3]
	s_barrier
	s_setprio 0
	s_branch .Lpeel_mid_p4
	s_nop 0
	s_nop 0
	s_nop 0
	s_nop 0
	s_nop 0
	s_nop 0
.LBB0_672:
	ds_read_b128 v[128:131], v185
	ds_read_b128 v[132:135], v185 offset:1024
	ds_read_b128 v[136:139], v185 offset:2048
	ds_read_b128 v[140:143], v185 offset:3072
	ds_read_b128 v[162:165], v186
	ds_read_b128 v[166:169], v186 offset:1024
	ds_read_b128 v[170:173], v186 offset:2048
	ds_read_b128 v[174:177], v186 offset:3072
	s_add_u32 s38, s6, 0xfff80080
	s_addc_u32 s39, s7, -1
	s_cmp_eq_u32 s56, 28
	s_cselect_b32 s41, s27, s39
	s_cselect_b32 s40, s26, s38
	s_cselect_b32 s39, s23, s25
	s_cselect_b32 s38, s22, s5
	v_lshl_add_u64 v[182:183], s[6:7], 0, v[158:159]
	s_add_i32 m0, s42, 0xc000
	ds_read_b128 v[178:181], v188
	ds_read_b128 v[192:195], v188 offset:1024
	ds_read_b128 v[196:199], v188 offset:2048
	ds_read_b128 v[200:203], v188 offset:3072
	ds_read_b128 v[204:207], v188 offset:4096
	ds_read_b128 v[208:211], v188 offset:5120
	ds_read_b128 v[212:215], v188 offset:6144
	ds_read_b128 v[216:219], v188 offset:7168
	global_load_lds_dwordx4 v[182:183], off
	v_lshl_add_u64 v[182:183], s[6:7], 0, v[160:161]
	s_add_i32 m0, s42, 0xe000
	s_nop 0
	global_load_lds_dwordx4 v[182:183], off
	s_waitcnt vmcnt(8)
	s_waitcnt lgkmcnt(0)
	s_waitcnt lgkmcnt(0)
	s_setprio 1
	s_barrier
	v_mfma_f32_16x16x32_bf16 v[124:127], v[128:131], v[178:181], v[124:127]
	v_mfma_f32_16x16x32_bf16 v[120:123], v[136:139], v[178:181], v[120:123]
	v_mfma_f32_16x16x32_bf16 v[108:111], v[128:131], v[196:199], v[108:111]
	v_mfma_f32_16x16x32_bf16 v[104:107], v[136:139], v[196:199], v[104:107]
	v_mfma_f32_16x16x32_bf16 v[92:95], v[128:131], v[204:207], v[92:95]
	v_mfma_f32_16x16x32_bf16 v[88:91], v[136:139], v[204:207], v[88:91]
	v_mfma_f32_16x16x32_bf16 v[76:79], v[128:131], v[212:215], v[76:79]
	v_mfma_f32_16x16x32_bf16 v[72:75], v[136:139], v[212:215], v[72:75]
	v_mfma_f32_16x16x32_bf16 v[124:127], v[132:135], v[192:195], v[124:127]
	v_mfma_f32_16x16x32_bf16 v[120:123], v[140:143], v[192:195], v[120:123]
	v_mfma_f32_16x16x32_bf16 v[108:111], v[132:135], v[200:203], v[108:111]
	v_mfma_f32_16x16x32_bf16 v[104:107], v[140:143], v[200:203], v[104:107]
	v_mfma_f32_16x16x32_bf16 v[92:95], v[132:135], v[208:211], v[92:95]
	v_mfma_f32_16x16x32_bf16 v[88:91], v[140:143], v[208:211], v[88:91]
	v_mfma_f32_16x16x32_bf16 v[76:79], v[132:135], v[216:219], v[76:79]
	v_mfma_f32_16x16x32_bf16 v[72:75], v[140:143], v[216:219], v[72:75]
	s_setprio 0
	s_setprio 1
	v_mfma_f32_16x16x32_bf16 v[116:119], v[162:165], v[178:181], v[116:119]
	v_mfma_f32_16x16x32_bf16 v[112:115], v[170:173], v[178:181], v[112:115]
	v_mfma_f32_16x16x32_bf16 v[100:103], v[162:165], v[196:199], v[100:103]
	v_mfma_f32_16x16x32_bf16 v[96:99], v[170:173], v[196:199], v[96:99]
	v_mfma_f32_16x16x32_bf16 v[84:87], v[162:165], v[204:207], v[84:87]
	v_mfma_f32_16x16x32_bf16 v[80:83], v[170:173], v[204:207], v[80:83]
	v_mfma_f32_16x16x32_bf16 v[68:71], v[162:165], v[212:215], v[68:71]
	v_mfma_f32_16x16x32_bf16 v[64:67], v[170:173], v[212:215], v[64:67]
	v_mfma_f32_16x16x32_bf16 v[116:119], v[166:169], v[192:195], v[116:119]
	v_mfma_f32_16x16x32_bf16 v[112:115], v[174:177], v[192:195], v[112:115]
	v_mfma_f32_16x16x32_bf16 v[100:103], v[166:169], v[200:203], v[100:103]
	v_mfma_f32_16x16x32_bf16 v[96:99], v[174:177], v[200:203], v[96:99]
	v_mfma_f32_16x16x32_bf16 v[84:87], v[166:169], v[208:211], v[84:87]
	v_mfma_f32_16x16x32_bf16 v[80:83], v[174:177], v[208:211], v[80:83]
	v_mfma_f32_16x16x32_bf16 v[68:71], v[166:169], v[216:219], v[68:71]
	v_mfma_f32_16x16x32_bf16 v[64:67], v[174:177], v[216:219], v[64:67]
	s_barrier
	s_setprio 0
	s_add_i32 s57, s51, s35
	v_lshl_add_u64 v[182:183], s[38:39], 0, v[148:149]
	s_mov_b32 m0, s57
	ds_read_b128 v[178:181], v188 offset:16384
	ds_read_b128 v[192:195], v188 offset:17408
	ds_read_b128 v[196:199], v188 offset:18432
	ds_read_b128 v[200:203], v188 offset:19456
	ds_read_b128 v[204:207], v188 offset:20480
	ds_read_b128 v[208:211], v188 offset:21504
	ds_read_b128 v[212:215], v188 offset:22528
	ds_read_b128 v[216:219], v188 offset:23552
	global_load_lds_dwordx4 v[182:183], off
	s_add_i32 m0, s57, 0x2000
	s_add_u32 s58, s38, 0x80000
	v_lshl_add_u64 v[220:221], s[38:39], 0, v[144:145]
	s_addc_u32 s59, s39, 0
	s_add_i32 s57, s52, s35
	global_load_lds_dwordx4 v[220:221], off
	v_lshl_add_u64 v[222:223], s[58:59], 0, v[148:149]
	s_mov_b32 m0, s57
	v_lshl_add_u64 v[224:225], s[40:41], 0, v[146:147]
	global_load_lds_dwordx4 v[222:223], off
	v_lshl_add_u64 v[222:223], s[58:59], 0, v[144:145]
	s_add_i32 m0, s57, 0x2000
	s_nop 0
	global_load_lds_dwordx4 v[222:223], off
	v_lshl_add_u64 v[222:223], s[40:41], 0, v[150:151]
	s_mov_b32 m0, s42
	s_nop 0
	global_load_lds_dwordx4 v[222:223], off
	s_mov_b32 m0, s43
	s_nop 0
	global_load_lds_dwordx4 v[224:225], off
	s_waitcnt vmcnt(8)
	s_waitcnt lgkmcnt(0)
	s_waitcnt lgkmcnt(0)
	s_setprio 1
	s_barrier
	v_mfma_f32_16x16x32_bf16 v[60:63], v[128:131], v[178:181], v[60:63]
	v_mfma_f32_16x16x32_bf16 v[56:59], v[136:139], v[178:181], v[56:59]
	v_mfma_f32_16x16x32_bf16 v[44:47], v[128:131], v[196:199], v[44:47]
	v_mfma_f32_16x16x32_bf16 v[40:43], v[136:139], v[196:199], v[40:43]
	v_mfma_f32_16x16x32_bf16 v[28:31], v[128:131], v[204:207], v[28:31]
	v_mfma_f32_16x16x32_bf16 v[24:27], v[136:139], v[204:207], v[24:27]
	v_mfma_f32_16x16x32_bf16 v[12:15], v[128:131], v[212:215], v[12:15]
	v_mfma_f32_16x16x32_bf16 v[8:11], v[136:139], v[212:215], v[8:11]
	v_mfma_f32_16x16x32_bf16 v[60:63], v[132:135], v[192:195], v[60:63]
	v_mfma_f32_16x16x32_bf16 v[56:59], v[140:143], v[192:195], v[56:59]
	v_mfma_f32_16x16x32_bf16 v[44:47], v[132:135], v[200:203], v[44:47]
	v_mfma_f32_16x16x32_bf16 v[40:43], v[140:143], v[200:203], v[40:43]
	v_mfma_f32_16x16x32_bf16 v[28:31], v[132:135], v[208:211], v[28:31]
	v_mfma_f32_16x16x32_bf16 v[24:27], v[140:143], v[208:211], v[24:27]
	v_mfma_f32_16x16x32_bf16 v[12:15], v[132:135], v[216:219], v[12:15]
	v_mfma_f32_16x16x32_bf16 v[8:11], v[140:143], v[216:219], v[8:11]
	s_setprio 0
	s_setprio 1
	v_mfma_f32_16x16x32_bf16 v[52:55], v[162:165], v[178:181], v[52:55]
	v_mfma_f32_16x16x32_bf16 v[48:51], v[170:173], v[178:181], v[48:51]
	v_mfma_f32_16x16x32_bf16 v[36:39], v[162:165], v[196:199], v[36:39]
	v_mfma_f32_16x16x32_bf16 v[32:35], v[170:173], v[196:199], v[32:35]
	v_mfma_f32_16x16x32_bf16 v[20:23], v[162:165], v[204:207], v[20:23]
	v_mfma_f32_16x16x32_bf16 v[16:19], v[170:173], v[204:207], v[16:19]
	v_mfma_f32_16x16x32_bf16 v[4:7], v[162:165], v[212:215], v[4:7]
	v_mfma_f32_16x16x32_bf16 v[0:3], v[170:173], v[212:215], v[0:3]
	v_mfma_f32_16x16x32_bf16 v[52:55], v[166:169], v[192:195], v[52:55]
	v_mfma_f32_16x16x32_bf16 v[48:51], v[174:177], v[192:195], v[48:51]
	v_mfma_f32_16x16x32_bf16 v[36:39], v[166:169], v[200:203], v[36:39]
	v_mfma_f32_16x16x32_bf16 v[32:35], v[174:177], v[200:203], v[32:35]
	v_mfma_f32_16x16x32_bf16 v[20:23], v[166:169], v[208:211], v[20:23]
	v_mfma_f32_16x16x32_bf16 v[16:19], v[174:177], v[208:211], v[16:19]
	v_mfma_f32_16x16x32_bf16 v[4:7], v[166:169], v[216:219], v[4:7]
	v_mfma_f32_16x16x32_bf16 v[0:3], v[174:177], v[216:219], v[0:3]
	s_barrier
	s_setprio 0
